# static s_setprio 1 for waves 0-3 during the attention units (other half, for comparison)
# baseline (speedup 1.0000x reference)
.LBB0_385:
	s_cmp_ge_u32 s28, 4
	s_cbranch_scc1 .Lprio_done
	s_setprio 1
